# attention: softmax (VALU) half runs at s_setprio 1, MFMA half at 0
# baseline (speedup 1.0000x reference)
; __device__ __forceinline__ int ltid() { int t = threadIdx.x; asm volatile("" : "+v"(t)); return t; }
; __device__ __forceinline__ void qkt(f32x16& p0, f32x16& p1, const unsigned char* Ks, const i32x8* qr, int r32, int hi) {
;   p0 = f32x16{}; p1 = f32x16{};
; #pragma unroll
;   for (int m = 0; m < 3; ++m) { const int cb = m * 64 + hi * 32;
;     const u32x4 a0 = *reinterpret_cast<const u32x4*>(Ks + KSWZ(r32, cb)), a1 = *reinterpret_cast<const u32x4*>(Ks + KSWZ(r32, cb) + 16);
;     const u32x4 c0 = *reinterpret_cast<const u32x4*>(Ks + KSWZ(32 + r32, cb)), c1 = *reinterpret_cast<const u32x4*>(Ks + KSWZ(32 + r32, cb) + 16);
;     const i32x8 b0 = {(int)a0.x, (int)a0.y, (int)a0.z, (int)a0.w, (int)a1.x, (int)a1.y, (int)a1.z, (int)a1.w};
;     const i32x8 b1 = {(int)c0.x, (int)c0.y, (int)c0.z, (int)c0.w, (int)c1.x, (int)c1.y, (int)c1.z, (int)c1.w};
;     p0 = __builtin_amdgcn_mfma_scale_f32_32x32x64_f8f6f4(b0, qr[m], p0, 0, 0, 0, 0x7F7F7F7F, 0, 0x7F7F7F7F);
;     p1 = __builtin_amdgcn_mfma_scale_f32_32x32x64_f8f6f4(b1, qr[m], p1, 0, 0, 0, 0x7F7F7F7F, 0, 0x7F7F7F7F); }
; }
; __device__ __forceinline__ void pv_d0(f32x16* o, const unsigned char* Vs, const i32x8& pa, int r32, int hi) {
; #pragma unroll
;   for (int d0 = 0; d0 < 4; ++d0) { const unsigned char* vp = Vs + (32 * d0 + r32) * 80 + hi * 32;
;     const u32x4 a0 = *reinterpret_cast<const u32x4*>(vp), a1 = *reinterpret_cast<const u32x4*>(vp + 16);
;     const i32x8 vb = {(int)a0.x, (int)a0.y, (int)a0.z, (int)a0.w, (int)a1.x, (int)a1.y, (int)a1.z, (int)a1.w};
;     o[d0] = __builtin_amdgcn_mfma_scale_f32_32x32x64_f8f6f4(pa, vb, o[d0], 0, 0, 0, 0x7A7A7A7A, 0, 0x7F7F7F7F); }
; }
; __device__ __forceinline__ void attn_body(const unsigned char* __restrict__ Qb, const unsigned char* __restrict__ Kh, const unsigned char* __restrict__ Vt,
;                                           bf16_t* __restrict__ Ob, int seq, char* lds) {
;   const int tid = ltid(), wid = tid >> 6, lane = tid & 63, r32 = lane & 31, hi = lane >> 5;
;   unsigned char* V_lds = (unsigned char*)lds; unsigned char* K_lds = (unsigned char*)(lds + 3 * SHM_V);
;   float* ws = (float*)(lds + 3 * SHM_V + 3 * SHM_K) + wid * 64; float* li_l = ws; float* al_l = ws + 32;
;   float m_reg = -1e30f, l_reg = 0; f32x16 o[4] = {}; i32x8 qr[3];
;   const unsigned char* Qw = Qb + (long)(wid * QBLK + r32) * 192 + hi * 32;
; #pragma unroll
.Latt_loop:
	s_cmp_eq_u32 s6, 0
	s_cbranch_scc1 .Latt_m_first
	s_setprio 0
	s_add_u32 s4, s6, 2
	ds_read_b128 v[176:179], v221 offset:30720
	ds_read_b128 v[180:183], v221 offset:30736
	ds_read_b128 v[184:187], v221 offset:33280
	ds_read_b128 v[188:191], v221 offset:33296
	s_waitcnt lgkmcnt(4)
	v_mfma_scale_f32_32x32x64_f8f6f4 v[64:79], v[128:135], v[96:103], v[160:175], v235, v201 op_sel_hi:[0,0,0]
	ds_read_b128 v[128:131], v220 offset:128
	ds_read_b128 v[132:135], v220 offset:144
	v_mfma_scale_f32_32x32x64_f8f6f4 v[80:95], v[136:143], v[96:103], v[160:175], v235, v201 op_sel_hi:[0,0,0]
	ds_read_b128 v[136:139], v220 offset:6784
	ds_read_b128 v[140:143], v220 offset:6800
	s_cmp_lt_u32 s4, 128
	s_cbranch_scc0 .Latt_ms0_nowr
	s_waitcnt vmcnt(0)
	ds_write2_b32 v225, v202, v204 offset1:1
	ds_write2_b32 v225, v203, v205 offset0:8 offset1:9
	ds_write_b128 v218, v[206:209] offset:26624
	s_cmp_lt_u32 s12, 4
	s_cbranch_scc0 .Latt_ms0_w1
	ds_write_b128 v219, v[210:213] offset:26624

; __device__ __forceinline__ void partialSM(f32x16& p0, f32x16& p1, float& m_reg, float& mn, float& alpha) {
;   constexpr float C = SCALE * 1.4426950408889634f;
;   float pmax = p0[0]; for (int r = 1; r < 16; ++r) pmax = fmaxf(pmax, p0[r]); for (int r = 0; r < 16; ++r) pmax = fmaxf(pmax, p1[r]);
;   { auto rr = __builtin_amdgcn_permlane32_swap(__float_as_uint(pmax), __float_as_uint(pmax), false, false);
;     pmax = fmaxf(__uint_as_float(rr[0]), __uint_as_float(rr[1])); }
;   if (__builtin_expect(__all(pmax - m_reg <= THR / SCALE), 1)) { mn = m_reg; alpha = 1.f; }
.Latt_m_nobar_0:
	s_setprio 1
	v_max3_f32 v228, v64, v65, v66
	v_max3_f32 v229, v80, v81, v82
	v_max3_f32 v228, v228, v67, v68
	v_max3_f32 v229, v229, v83, v84
	v_max3_f32 v228, v228, v69, v70
	v_max3_f32 v229, v229, v85, v86
	v_max3_f32 v228, v228, v71, v72
	v_max3_f32 v229, v229, v87, v88
	v_max3_f32 v228, v228, v73, v74
	v_max3_f32 v229, v229, v89, v90
	v_max3_f32 v228, v228, v75, v76
	v_max3_f32 v229, v229, v91, v92
	v_max3_f32 v228, v228, v77, v78
	v_max3_f32 v229, v229, v93, v94
	v_max3_f32 v228, v228, v79, v95
	v_max_f32_e32 v228, v228, v229
	s_mov_b32 s5, 0
	v_cmp_ge_f32_e32 vcc, s13, v228
	v_mov_b32_e32 v226, 1.0
	s_cmp_eq_u32 s6, 0
	s_cbranch_scc1 .Latt_rare
	s_cmp_eq_u64 vcc, exec
	s_cbranch_scc0 .Latt_rare

; __device__ __forceinline__ void qkt(f32x16& p0, f32x16& p1, const unsigned char* Ks, const i32x8* qr, int r32, int hi) {
;   p0 = f32x16{}; p1 = f32x16{};
; #pragma unroll
;   for (int m = 0; m < 3; ++m) { const int cb = m * 64 + hi * 32;
;     const u32x4 a0 = *reinterpret_cast<const u32x4*>(Ks + KSWZ(r32, cb)), a1 = *reinterpret_cast<const u32x4*>(Ks + KSWZ(r32, cb) + 16);
;     const u32x4 c0 = *reinterpret_cast<const u32x4*>(Ks + KSWZ(32 + r32, cb)), c1 = *reinterpret_cast<const u32x4*>(Ks + KSWZ(32 + r32, cb) + 16);
;     const i32x8 b0 = {(int)a0.x, (int)a0.y, (int)a0.z, (int)a0.w, (int)a1.x, (int)a1.y, (int)a1.z, (int)a1.w};
;     const i32x8 b1 = {(int)c0.x, (int)c0.y, (int)c0.z, (int)c0.w, (int)c1.x, (int)c1.y, (int)c1.z, (int)c1.w};
;     p0 = __builtin_amdgcn_mfma_scale_f32_32x32x64_f8f6f4(b0, qr[m], p0, 0, 0, 0, 0x7F7F7F7F, 0, 0x7F7F7F7F);
;     p1 = __builtin_amdgcn_mfma_scale_f32_32x32x64_f8f6f4(b1, qr[m], p1, 0, 0, 0, 0x7F7F7F7F, 0, 0x7F7F7F7F); }
.Latt_v_nobar_0:
	s_add_u32 s6, s6, 1
	s_setprio 0
	s_add_u32 s4, s6, 2
	ds_read_b128 v[176:179], v221 offset:0
	ds_read_b128 v[180:183], v221 offset:16
	ds_read_b128 v[184:187], v221 offset:2560
	ds_read_b128 v[188:191], v221 offset:2576
	s_waitcnt lgkmcnt(4)
	v_mfma_scale_f32_32x32x64_f8f6f4 v[64:79], v[128:135], v[96:103], v[160:175], v235, v201 op_sel_hi:[0,0,0]
	ds_read_b128 v[128:131], v220 offset:13440
	ds_read_b128 v[132:135], v220 offset:13456
	v_mfma_scale_f32_32x32x64_f8f6f4 v[80:95], v[136:143], v[96:103], v[160:175], v235, v201 op_sel_hi:[0,0,0]
	ds_read_b128 v[136:139], v220 offset:20096
	ds_read_b128 v[140:143], v220 offset:20112
	s_cmp_lt_u32 s4, 128
	s_cbranch_scc0 .Latt_ms1_nowr
	v_add_u32_e32 v228, 30720, v217
	s_waitcnt vmcnt(0)
	ds_write2_b32 v228, v202, v204 offset1:1
	ds_write2_b32 v228, v203, v205 offset0:8 offset1:9
	ds_write_b128 v218, v[206:209] offset:39936
	s_cmp_lt_u32 s12, 4
	s_cbranch_scc0 .Latt_ms1_w1
	ds_write_b128 v219, v[210:213] offset:39936

; __device__ __forceinline__ void partialSM(f32x16& p0, f32x16& p1, float& m_reg, float& mn, float& alpha) {
;   constexpr float C = SCALE * 1.4426950408889634f;
;   float pmax = p0[0]; for (int r = 1; r < 16; ++r) pmax = fmaxf(pmax, p0[r]); for (int r = 0; r < 16; ++r) pmax = fmaxf(pmax, p1[r]);
;   { auto rr = __builtin_amdgcn_permlane32_swap(__float_as_uint(pmax), __float_as_uint(pmax), false, false);
;     pmax = fmaxf(__uint_as_float(rr[0]), __uint_as_float(rr[1])); }
;   if (__builtin_expect(__all(pmax - m_reg <= THR / SCALE), 1)) { mn = m_reg; alpha = 1.f; }
.Latt_m_nobar_1:
	s_setprio 1
	v_max3_f32 v228, v64, v65, v66
	v_max3_f32 v229, v80, v81, v82
	v_max3_f32 v228, v228, v67, v68
	v_max3_f32 v229, v229, v83, v84
	v_max3_f32 v228, v228, v69, v70
	v_max3_f32 v229, v229, v85, v86
	v_max3_f32 v228, v228, v71, v72
	v_max3_f32 v229, v229, v87, v88
	v_max3_f32 v228, v228, v73, v74
	v_max3_f32 v229, v229, v89, v90
	v_max3_f32 v228, v228, v75, v76
	v_max3_f32 v229, v229, v91, v92
	v_max3_f32 v228, v228, v77, v78
	v_max3_f32 v229, v229, v93, v94
	v_max3_f32 v228, v228, v79, v95
	v_max_f32_e32 v228, v228, v229
	s_mov_b32 s5, 1
	v_cmp_ge_f32_e32 vcc, s13, v228
	v_mov_b32_e32 v226, 1.0
	s_cmp_eq_u64 vcc, exec
	s_cbranch_scc0 .Latt_rare

; __device__ __forceinline__ void qkt(f32x16& p0, f32x16& p1, const unsigned char* Ks, const i32x8* qr, int r32, int hi) {
;   p0 = f32x16{}; p1 = f32x16{};
; #pragma unroll
;   for (int m = 0; m < 3; ++m) { const int cb = m * 64 + hi * 32;
;     const u32x4 a0 = *reinterpret_cast<const u32x4*>(Ks + KSWZ(r32, cb)), a1 = *reinterpret_cast<const u32x4*>(Ks + KSWZ(r32, cb) + 16);
;     const u32x4 c0 = *reinterpret_cast<const u32x4*>(Ks + KSWZ(32 + r32, cb)), c1 = *reinterpret_cast<const u32x4*>(Ks + KSWZ(32 + r32, cb) + 16);
;     const i32x8 b0 = {(int)a0.x, (int)a0.y, (int)a0.z, (int)a0.w, (int)a1.x, (int)a1.y, (int)a1.z, (int)a1.w};
;     const i32x8 b1 = {(int)c0.x, (int)c0.y, (int)c0.z, (int)c0.w, (int)c1.x, (int)c1.y, (int)c1.z, (int)c1.w};
;     p0 = __builtin_amdgcn_mfma_scale_f32_32x32x64_f8f6f4(b0, qr[m], p0, 0, 0, 0, 0x7F7F7F7F, 0, 0x7F7F7F7F);
;     p1 = __builtin_amdgcn_mfma_scale_f32_32x32x64_f8f6f4(b1, qr[m], p1, 0, 0, 0, 0x7F7F7F7F, 0, 0x7F7F7F7F); }
.Latt_v_nobar_1:
	s_add_u32 s6, s6, 1
	s_setprio 0
	s_add_u32 s4, s6, 2
	ds_read_b128 v[176:179], v221 offset:10240
	ds_read_b128 v[180:183], v221 offset:10256
	ds_read_b128 v[184:187], v221 offset:12800
	ds_read_b128 v[188:191], v221 offset:12816
	s_waitcnt lgkmcnt(4)
	v_mfma_scale_f32_32x32x64_f8f6f4 v[64:79], v[128:135], v[96:103], v[160:175], v235, v201 op_sel_hi:[0,0,0]
	ds_read_b128 v[128:131], v220 offset:26752
	ds_read_b128 v[132:135], v220 offset:26768
	v_mfma_scale_f32_32x32x64_f8f6f4 v[80:95], v[136:143], v[96:103], v[160:175], v235, v201 op_sel_hi:[0,0,0]
	ds_read_b128 v[136:139], v220 offset:33408
	ds_read_b128 v[140:143], v220 offset:33424
	s_cmp_lt_u32 s4, 128
	s_cbranch_scc0 .Latt_ms2_nowr
	s_waitcnt vmcnt(0)
	ds_write2_b32 v217, v202, v204 offset1:1
	ds_write2_b32 v217, v203, v205 offset0:8 offset1:9
	ds_write_b128 v218, v[206:209] offset:0
	s_cmp_lt_u32 s12, 4
	s_cbranch_scc0 .Latt_ms2_w1
	ds_write_b128 v219, v[210:213] offset:0

; __device__ __forceinline__ void partialSM(f32x16& p0, f32x16& p1, float& m_reg, float& mn, float& alpha) {
;   constexpr float C = SCALE * 1.4426950408889634f;
;   float pmax = p0[0]; for (int r = 1; r < 16; ++r) pmax = fmaxf(pmax, p0[r]); for (int r = 0; r < 16; ++r) pmax = fmaxf(pmax, p1[r]);
;   { auto rr = __builtin_amdgcn_permlane32_swap(__float_as_uint(pmax), __float_as_uint(pmax), false, false);
;     pmax = fmaxf(__uint_as_float(rr[0]), __uint_as_float(rr[1])); }
;   if (__builtin_expect(__all(pmax - m_reg <= THR / SCALE), 1)) { mn = m_reg; alpha = 1.f; }
.Latt_m_nobar_2:
	s_setprio 1
	v_max3_f32 v228, v64, v65, v66
	v_max3_f32 v229, v80, v81, v82
	v_max3_f32 v228, v228, v67, v68
	v_max3_f32 v229, v229, v83, v84
	v_max3_f32 v228, v228, v69, v70
	v_max3_f32 v229, v229, v85, v86
	v_max3_f32 v228, v228, v71, v72
	v_max3_f32 v229, v229, v87, v88
	v_max3_f32 v228, v228, v73, v74
	v_max3_f32 v229, v229, v89, v90
	v_max3_f32 v228, v228, v75, v76
	v_max3_f32 v229, v229, v91, v92
	v_max3_f32 v228, v228, v77, v78
	v_max3_f32 v229, v229, v93, v94
	v_max3_f32 v228, v228, v79, v95
	v_max_f32_e32 v228, v228, v229
	s_mov_b32 s5, 2
	v_cmp_ge_f32_e32 vcc, s13, v228
	v_mov_b32_e32 v226, 1.0
	s_cmp_eq_u64 vcc, exec
	s_cbranch_scc0 .Latt_rare

; __device__ __forceinline__ void qkt(f32x16& p0, f32x16& p1, const unsigned char* Ks, const i32x8* qr, int r32, int hi) {
;   p0 = f32x16{}; p1 = f32x16{};
; #pragma unroll
;   for (int m = 0; m < 3; ++m) { const int cb = m * 64 + hi * 32;
;     const u32x4 a0 = *reinterpret_cast<const u32x4*>(Ks + KSWZ(r32, cb)), a1 = *reinterpret_cast<const u32x4*>(Ks + KSWZ(r32, cb) + 16);
;     const u32x4 c0 = *reinterpret_cast<const u32x4*>(Ks + KSWZ(32 + r32, cb)), c1 = *reinterpret_cast<const u32x4*>(Ks + KSWZ(32 + r32, cb) + 16);
;     const i32x8 b0 = {(int)a0.x, (int)a0.y, (int)a0.z, (int)a0.w, (int)a1.x, (int)a1.y, (int)a1.z, (int)a1.w};
;     const i32x8 b1 = {(int)c0.x, (int)c0.y, (int)c0.z, (int)c0.w, (int)c1.x, (int)c1.y, (int)c1.z, (int)c1.w};
;     p0 = __builtin_amdgcn_mfma_scale_f32_32x32x64_f8f6f4(b0, qr[m], p0, 0, 0, 0, 0x7F7F7F7F, 0, 0x7F7F7F7F);
;     p1 = __builtin_amdgcn_mfma_scale_f32_32x32x64_f8f6f4(b1, qr[m], p1, 0, 0, 0, 0x7F7F7F7F, 0, 0x7F7F7F7F); }
.Latt_v_nobar_2:
	s_add_u32 s6, s6, 1
	s_setprio 0
	s_add_u32 s4, s6, 2
	ds_read_b128 v[176:179], v221 offset:20480
	ds_read_b128 v[180:183], v221 offset:20496
	ds_read_b128 v[184:187], v221 offset:23040
	ds_read_b128 v[188:191], v221 offset:23056
	s_waitcnt lgkmcnt(4)
	v_mfma_scale_f32_32x32x64_f8f6f4 v[64:79], v[128:135], v[96:103], v[160:175], v235, v201 op_sel_hi:[0,0,0]
	ds_read_b128 v[128:131], v220 offset:40064
	ds_read_b128 v[132:135], v220 offset:40080
	v_mfma_scale_f32_32x32x64_f8f6f4 v[80:95], v[136:143], v[96:103], v[160:175], v235, v201 op_sel_hi:[0,0,0]
	ds_read_b128 v[136:139], v220 offset:46720
	ds_read_b128 v[140:143], v220 offset:46736
	s_cmp_lt_u32 s4, 128
	s_cbranch_scc0 .Latt_ms3_nowr
	s_waitcnt vmcnt(0)
	ds_write2_b32 v224, v202, v204 offset1:1
	ds_write2_b32 v224, v203, v205 offset0:8 offset1:9
	ds_write_b128 v218, v[206:209] offset:13312
	s_cmp_lt_u32 s12, 4
	s_cbranch_scc0 .Latt_ms3_w1
	ds_write_b128 v219, v[210:213] offset:13312

; __device__ __forceinline__ void partialSM(f32x16& p0, f32x16& p1, float& m_reg, float& mn, float& alpha) {
;   constexpr float C = SCALE * 1.4426950408889634f;
;   float pmax = p0[0]; for (int r = 1; r < 16; ++r) pmax = fmaxf(pmax, p0[r]); for (int r = 0; r < 16; ++r) pmax = fmaxf(pmax, p1[r]);
;   { auto rr = __builtin_amdgcn_permlane32_swap(__float_as_uint(pmax), __float_as_uint(pmax), false, false);
;     pmax = fmaxf(__uint_as_float(rr[0]), __uint_as_float(rr[1])); }
;   if (__builtin_expect(__all(pmax - m_reg <= THR / SCALE), 1)) { mn = m_reg; alpha = 1.f; }
.Latt_m_nobar_3:
	s_setprio 1
	v_max3_f32 v228, v64, v65, v66
	v_max3_f32 v229, v80, v81, v82
	v_max3_f32 v228, v228, v67, v68
	v_max3_f32 v229, v229, v83, v84
	v_max3_f32 v228, v228, v69, v70
	v_max3_f32 v229, v229, v85, v86
	v_max3_f32 v228, v228, v71, v72
	v_max3_f32 v229, v229, v87, v88
	v_max3_f32 v228, v228, v73, v74
	v_max3_f32 v229, v229, v89, v90
	v_max3_f32 v228, v228, v75, v76
	v_max3_f32 v229, v229, v91, v92
	v_max3_f32 v228, v228, v77, v78
	v_max3_f32 v229, v229, v93, v94
	v_max3_f32 v228, v228, v79, v95
	v_max_f32_e32 v228, v228, v229
	s_mov_b32 s5, 3
	v_cmp_ge_f32_e32 vcc, s13, v228
	v_mov_b32_e32 v226, 1.0
	s_cmp_eq_u64 vcc, exec
	s_cbranch_scc0 .Latt_rare

; __device__ __forceinline__ bf16_t f2bf(float f) { return (bf16_t)(cvt_pk_bf16(f, 0.f) & 0xffffu); }
; #define SBAR() __builtin_amdgcn_sched_barrier(0)
; __device__ __forceinline__ int crow(int r, int hi) { return (r & 3) + 8 * (r >> 2) + 4 * hi; }
; __device__ __forceinline__ void attn_body(const unsigned char* __restrict__ Qb, const unsigned char* __restrict__ Kh, const unsigned char* __restrict__ Vt,
;                                           bf16_t* __restrict__ Ob, int seq, char* lds) {
;     ...
;   finishSM(pB0, pB1, alB, l_reg, pa); SBAR();
;   pv_d0(o, V_lds + sP * SHM_V, pa, r32, hi);
;     ...
;   if (hi == 0) li_l[r32] = l_reg; asm volatile("s_waitcnt lgkmcnt(0)" ::: "memory");
;   float rli[16];
; #pragma unroll
;   for (int r = 0; r < 16; ++r) rli[r] = 32.f * __builtin_amdgcn_rcpf(li_l[crow(r, hi)]);
;   bf16_t* Ow = Ob + (long)(wid * QBLK) * LDO;
; #pragma unroll
;   for (int r = 0; r < 16; ++r) { int orow = crow(r, hi);
;     for (int d0 = 0; d0 < 4; ++d0) Ow[(long)orow * LDO + d0 * 32 + r32] = f2bf(o[d0][r] * rli[r]); }
.Latt_tail:
	s_setprio 0
	ds_read_b128 v[176:179], v221 offset:30720
	ds_read_b128 v[180:183], v221 offset:30736
	ds_read_b128 v[184:187], v221 offset:33280
	ds_read_b128 v[188:191], v221 offset:33296
	s_waitcnt lgkmcnt(2)
	v_mfma_scale_f32_32x32x64_f8f6f4 v[0:15], v[120:127], v[176:183], v[0:15], v237, v235 op_sel_hi:[0,0,0]
	ds_read_b128 v[176:179], v221 offset:35840
	ds_read_b128 v[180:183], v221 offset:35856
	s_waitcnt lgkmcnt(2)
	v_mfma_scale_f32_32x32x64_f8f6f4 v[16:31], v[120:127], v[184:191], v[16:31], v237, v235 op_sel_hi:[0,0,0]
	ds_read_b128 v[184:187], v221 offset:38400
	ds_read_b128 v[188:191], v221 offset:38416
	s_waitcnt lgkmcnt(2)
	v_mfma_scale_f32_32x32x64_f8f6f4 v[32:47], v[120:127], v[176:183], v[32:47], v237, v235 op_sel_hi:[0,0,0]
	s_waitcnt lgkmcnt(0)
	v_mfma_scale_f32_32x32x64_f8f6f4 v[48:63], v[120:127], v[184:191], v[48:63], v237, v235 op_sel_hi:[0,0,0]
	v_mov_b32_e32 v229, v194
	s_nop 1
	v_permlane32_swap_b32_e32 v194, v229
	v_add_f32_e32 v194, v194, v229
	s_mov_b32 exec_hi, 0
	ds_write_b32 v222, v194
	s_mov_b64 exec, -1
	s_waitcnt lgkmcnt(0)
	ds_read_b128 v[64:67], v223 offset:0
	ds_read_b128 v[68:71], v223 offset:32
	ds_read_b128 v[72:75], v223 offset:64
	ds_read_b128 v[76:79], v223 offset:96
	v_lshrrev_b32_e32 v231, 6, v192
	v_bfe_u32 v229, v192, 5, 1
	v_lshl_add_u32 v231, v231, 3, v229
	v_and_b32_e32 v201, 31, v192
	v_lshlrev_b32_e32 v231, 14, v231
	v_lshl_add_u32 v225, v201, 1, v231
	s_waitcnt lgkmcnt(0)
	v_rcp_f32_e32 v64, v64
	v_rcp_f32_e32 v65, v65
	v_rcp_f32_e32 v66, v66
	v_rcp_f32_e32 v67, v67
	v_rcp_f32_e32 v68, v68
	v_rcp_f32_e32 v69, v69
	v_rcp_f32_e32 v70, v70
	v_rcp_f32_e32 v71, v71
	v_rcp_f32_e32 v72, v72
	v_rcp_f32_e32 v73, v73
	v_rcp_f32_e32 v74, v74
	v_rcp_f32_e32 v75, v75
	v_rcp_f32_e32 v76, v76
	v_rcp_f32_e32 v77, v77
	v_rcp_f32_e32 v78, v78
	v_rcp_f32_e32 v79, v79
	s_nop 0
	v_mul_f32_e32 v64, 0x42000000, v64
	v_mul_f32_e32 v65, 0x42000000, v65
	v_mul_f32_e32 v66, 0x42000000, v66
	v_mul_f32_e32 v67, 0x42000000, v67
	v_mul_f32_e32 v68, 0x42000000, v68
	v_mul_f32_e32 v69, 0x42000000, v69
	v_mul_f32_e32 v70, 0x42000000, v70
	v_mul_f32_e32 v71, 0x42000000, v71
	v_mul_f32_e32 v72, 0x42000000, v72
	v_mul_f32_e32 v73, 0x42000000, v73
	v_mul_f32_e32 v74, 0x42000000, v74
	v_mul_f32_e32 v75, 0x42000000, v75
	v_mul_f32_e32 v76, 0x42000000, v76
	v_mul_f32_e32 v77, 0x42000000, v77
	v_mul_f32_e32 v78, 0x42000000, v78
	v_mul_f32_e32 v79, 0x42000000, v79
	s_nop 7
	v_mul_f32_e32 v80, v0, v64
	v_cvt_pk_bf16_f32 v80, v80, v195
	v_mul_f32_e32 v81, v16, v64
	v_cvt_pk_bf16_f32 v81, v81, v195
	v_mul_f32_e32 v82, v32, v64
	v_cvt_pk_bf16_f32 v82, v82, v195
	v_mul_f32_e32 v83, v48, v64
	v_cvt_pk_bf16_f32 v83, v83, v195
	global_store_short v225, v80, s[16:17] offset:0
	global_store_short v225, v81, s[16:17] offset:64
	global_store_short v225, v82, s[16:17] offset:128
	global_store_short v225, v83, s[16:17] offset:192
	v_add_u32_e32 v224, 0x1000, v225
	v_mul_f32_e32 v80, v1, v65
	v_cvt_pk_bf16_f32 v80, v80, v195
	v_mul_f32_e32 v81, v17, v65
	v_cvt_pk_bf16_f32 v81, v81, v195
	v_mul_f32_e32 v82, v33, v65
	v_cvt_pk_bf16_f32 v82, v82, v195
	v_mul_f32_e32 v83, v49, v65
	v_cvt_pk_bf16_f32 v83, v83, v195
	global_store_short v224, v80, s[16:17] offset:0
	global_store_short v224, v81, s[16:17] offset:64
	global_store_short v224, v82, s[16:17] offset:128
	global_store_short v224, v83, s[16:17] offset:192
	v_add_u32_e32 v224, 0x2000, v225
	v_mul_f32_e32 v80, v2, v66
	v_cvt_pk_bf16_f32 v80, v80, v195
	v_mul_f32_e32 v81, v18, v66
	v_cvt_pk_bf16_f32 v81, v81, v195
	v_mul_f32_e32 v82, v34, v66
	v_cvt_pk_bf16_f32 v82, v82, v195
	v_mul_f32_e32 v83, v50, v66
	v_cvt_pk_bf16_f32 v83, v83, v195
	global_store_short v224, v80, s[16:17] offset:0
	global_store_short v224, v81, s[16:17] offset:64
	global_store_short v224, v82, s[16:17] offset:128
	global_store_short v224, v83, s[16:17] offset:192
	v_add_u32_e32 v224, 0x3000, v225
	v_mul_f32_e32 v80, v3, v67
	v_cvt_pk_bf16_f32 v80, v80, v195
	v_mul_f32_e32 v81, v19, v67
	v_cvt_pk_bf16_f32 v81, v81, v195
	v_mul_f32_e32 v82, v35, v67
	v_cvt_pk_bf16_f32 v82, v82, v195
	v_mul_f32_e32 v83, v51, v67
	v_cvt_pk_bf16_f32 v83, v83, v195
	global_store_short v224, v80, s[16:17] offset:0
	global_store_short v224, v81, s[16:17] offset:64
	global_store_short v224, v82, s[16:17] offset:128
	global_store_short v224, v83, s[16:17] offset:192
	v_add_u32_e32 v224, 0x8000, v225
	v_mul_f32_e32 v80, v4, v68
	v_cvt_pk_bf16_f32 v80, v80, v195
	v_mul_f32_e32 v81, v20, v68
	v_cvt_pk_bf16_f32 v81, v81, v195
	v_mul_f32_e32 v82, v36, v68
	v_cvt_pk_bf16_f32 v82, v82, v195
	v_mul_f32_e32 v83, v52, v68
	v_cvt_pk_bf16_f32 v83, v83, v195
	global_store_short v224, v80, s[16:17] offset:0
	global_store_short v224, v81, s[16:17] offset:64
	global_store_short v224, v82, s[16:17] offset:128
	global_store_short v224, v83, s[16:17] offset:192
	v_add_u32_e32 v224, 0x9000, v225
	v_mul_f32_e32 v80, v5, v69
	v_cvt_pk_bf16_f32 v80, v80, v195
	v_mul_f32_e32 v81, v21, v69
	v_cvt_pk_bf16_f32 v81, v81, v195
	v_mul_f32_e32 v82, v37, v69
	v_cvt_pk_bf16_f32 v82, v82, v195
	v_mul_f32_e32 v83, v53, v69
	v_cvt_pk_bf16_f32 v83, v83, v195
	global_store_short v224, v80, s[16:17] offset:0
	global_store_short v224, v81, s[16:17] offset:64
; __device__ __forceinline__ bf16_t f2bf(float f) { return (bf16_t)(cvt_pk_bf16(f, 0.f) & 0xffffu); }
; __device__ __forceinline__ int crow(int r, int hi) { return (r & 3) + 8 * (r >> 2) + 4 * hi; }
; __device__ __forceinline__ void attn_body(const unsigned char* __restrict__ Qb, const unsigned char* __restrict__ Kh, const unsigned char* __restrict__ Vt,
;                                           bf16_t* __restrict__ Ob, int seq, char* lds) {
;     ...
;   for (int r = 0; r < 16; ++r) { int orow = crow(r, hi);
;     for (int d0 = 0; d0 < 4; ++d0) Ow[(long)orow * LDO + d0 * 32 + r32] = f2bf(o[d0][r] * rli[r]); }
;   asm volatile("s_waitcnt vmcnt(0)" ::: "memory");
;   __syncthreads();
; __global__ void __launch_bounds__(512) mega_fwd(Params p) {
;     ...
;             for (int it = bx; it < 256; it += G) { const int h = it & 7, qb = it >> 3;
;                 att::attn_body((const unsigned char*)B.Q + ((size_t)h * S_ + qb * 256) * 192, (const unsigned char*)B.K + (size_t)h * S_ * 192, (const unsigned char*)B.V + (size_t)h * 128 * S_,
;                                B.Y + (size_t)(qb * 256) * DM + 1024 + h * 128, S_, (char*)lds_raw); }
	global_store_short v224, v82, s[16:17] offset:128
	global_store_short v224, v83, s[16:17] offset:192
	v_add_u32_e32 v224, 0xa000, v225
	v_mul_f32_e32 v80, v6, v70
	v_cvt_pk_bf16_f32 v80, v80, v195
	v_mul_f32_e32 v81, v22, v70
	v_cvt_pk_bf16_f32 v81, v81, v195
	v_mul_f32_e32 v82, v38, v70
	v_cvt_pk_bf16_f32 v82, v82, v195
	v_mul_f32_e32 v83, v54, v70
	v_cvt_pk_bf16_f32 v83, v83, v195
	global_store_short v224, v80, s[16:17] offset:0
	global_store_short v224, v81, s[16:17] offset:64
	global_store_short v224, v82, s[16:17] offset:128
	global_store_short v224, v83, s[16:17] offset:192
	v_add_u32_e32 v224, 0xb000, v225
	v_mul_f32_e32 v80, v7, v71
	v_cvt_pk_bf16_f32 v80, v80, v195
	v_mul_f32_e32 v81, v23, v71
	v_cvt_pk_bf16_f32 v81, v81, v195
	v_mul_f32_e32 v82, v39, v71
	v_cvt_pk_bf16_f32 v82, v82, v195
	v_mul_f32_e32 v83, v55, v71
	v_cvt_pk_bf16_f32 v83, v83, v195
	global_store_short v224, v80, s[16:17] offset:0
	global_store_short v224, v81, s[16:17] offset:64
	global_store_short v224, v82, s[16:17] offset:128
	global_store_short v224, v83, s[16:17] offset:192
	v_add_u32_e32 v224, 0x10000, v225
	v_mul_f32_e32 v80, v8, v72
	v_cvt_pk_bf16_f32 v80, v80, v195
	v_mul_f32_e32 v81, v24, v72
	v_cvt_pk_bf16_f32 v81, v81, v195
	v_mul_f32_e32 v82, v40, v72
	v_cvt_pk_bf16_f32 v82, v82, v195
	v_mul_f32_e32 v83, v56, v72
	v_cvt_pk_bf16_f32 v83, v83, v195
	global_store_short v224, v80, s[16:17] offset:0
	global_store_short v224, v81, s[16:17] offset:64
	global_store_short v224, v82, s[16:17] offset:128
	global_store_short v224, v83, s[16:17] offset:192
	v_add_u32_e32 v224, 0x11000, v225
	v_mul_f32_e32 v80, v9, v73
	v_cvt_pk_bf16_f32 v80, v80, v195
	v_mul_f32_e32 v81, v25, v73
	v_cvt_pk_bf16_f32 v81, v81, v195
	v_mul_f32_e32 v82, v41, v73
	v_cvt_pk_bf16_f32 v82, v82, v195
	v_mul_f32_e32 v83, v57, v73
	v_cvt_pk_bf16_f32 v83, v83, v195
	global_store_short v224, v80, s[16:17] offset:0
	global_store_short v224, v81, s[16:17] offset:64
	global_store_short v224, v82, s[16:17] offset:128
	global_store_short v224, v83, s[16:17] offset:192
	v_add_u32_e32 v224, 0x12000, v225
	v_mul_f32_e32 v80, v10, v74
	v_cvt_pk_bf16_f32 v80, v80, v195
	v_mul_f32_e32 v81, v26, v74
	v_cvt_pk_bf16_f32 v81, v81, v195
	v_mul_f32_e32 v82, v42, v74
	v_cvt_pk_bf16_f32 v82, v82, v195
	v_mul_f32_e32 v83, v58, v74
	v_cvt_pk_bf16_f32 v83, v83, v195
	global_store_short v224, v80, s[16:17] offset:0
	global_store_short v224, v81, s[16:17] offset:64
	global_store_short v224, v82, s[16:17] offset:128
	global_store_short v224, v83, s[16:17] offset:192
	v_add_u32_e32 v224, 0x13000, v225
	v_mul_f32_e32 v80, v11, v75
	v_cvt_pk_bf16_f32 v80, v80, v195
	v_mul_f32_e32 v81, v27, v75
	v_cvt_pk_bf16_f32 v81, v81, v195
	v_mul_f32_e32 v82, v43, v75
	v_cvt_pk_bf16_f32 v82, v82, v195
	v_mul_f32_e32 v83, v59, v75
	v_cvt_pk_bf16_f32 v83, v83, v195
	global_store_short v224, v80, s[16:17] offset:0
	global_store_short v224, v81, s[16:17] offset:64
	global_store_short v224, v82, s[16:17] offset:128
	global_store_short v224, v83, s[16:17] offset:192
	v_add_u32_e32 v224, 0x18000, v225
	v_mul_f32_e32 v80, v12, v76
	v_cvt_pk_bf16_f32 v80, v80, v195
	v_mul_f32_e32 v81, v28, v76
	v_cvt_pk_bf16_f32 v81, v81, v195
	v_mul_f32_e32 v82, v44, v76
	v_cvt_pk_bf16_f32 v82, v82, v195
	v_mul_f32_e32 v83, v60, v76
	v_cvt_pk_bf16_f32 v83, v83, v195
	global_store_short v224, v80, s[16:17] offset:0
	global_store_short v224, v81, s[16:17] offset:64
	global_store_short v224, v82, s[16:17] offset:128
	global_store_short v224, v83, s[16:17] offset:192
	v_add_u32_e32 v224, 0x19000, v225
	v_mul_f32_e32 v80, v13, v77
	v_cvt_pk_bf16_f32 v80, v80, v195
	v_mul_f32_e32 v81, v29, v77
	v_cvt_pk_bf16_f32 v81, v81, v195
	v_mul_f32_e32 v82, v45, v77
	v_cvt_pk_bf16_f32 v82, v82, v195
	v_mul_f32_e32 v83, v61, v77
	v_cvt_pk_bf16_f32 v83, v83, v195
	global_store_short v224, v80, s[16:17] offset:0
	global_store_short v224, v81, s[16:17] offset:64
	global_store_short v224, v82, s[16:17] offset:128
	global_store_short v224, v83, s[16:17] offset:192
	v_add_u32_e32 v224, 0x1a000, v225
	v_mul_f32_e32 v80, v14, v78
	v_cvt_pk_bf16_f32 v80, v80, v195
	v_mul_f32_e32 v81, v30, v78
	v_cvt_pk_bf16_f32 v81, v81, v195
	v_mul_f32_e32 v82, v46, v78
	v_cvt_pk_bf16_f32 v82, v82, v195
	v_mul_f32_e32 v83, v62, v78
	v_cvt_pk_bf16_f32 v83, v83, v195
	global_store_short v224, v80, s[16:17] offset:0
	global_store_short v224, v81, s[16:17] offset:64
	global_store_short v224, v82, s[16:17] offset:128
	global_store_short v224, v83, s[16:17] offset:192
	v_add_u32_e32 v224, 0x1b000, v225
	v_mul_f32_e32 v80, v15, v79
	v_cvt_pk_bf16_f32 v80, v80, v195
	v_mul_f32_e32 v81, v31, v79
	v_cvt_pk_bf16_f32 v81, v81, v195
	v_mul_f32_e32 v82, v47, v79
	v_cvt_pk_bf16_f32 v82, v82, v195
	v_mul_f32_e32 v83, v63, v79
	v_cvt_pk_bf16_f32 v83, v83, v195
	global_store_short v224, v80, s[16:17] offset:0
	global_store_short v224, v81, s[16:17] offset:64
	global_store_short v224, v82, s[16:17] offset:128
	global_store_short v224, v83, s[16:17] offset:192
	s_waitcnt vmcnt(0)
	v_readlane_b32 s0, v252, 9
	s_nop 1
	s_add_i32 s25, s25, s0
	s_add_i32 s24, s24, s0
	s_cmpk_gt_i32 s25, 0xff
	s_waitcnt lgkmcnt(0)
	s_barrier
	v_readlane_b32 s1, v252, 10
	s_cbranch_scc1 .LBB0_297
	s_branch .LBB0_260
